# stacked: 4-set scan with early chunk barrier + static priority for waves 4-7 in the GEMM loop + GLOBAL instead of FLAT in the GEMM epilogue, on top of the prologue-deserialised version
# speedup vs baseline: 1.0251x; 1.0129x over previous
; DEVI float bf_lo(unsigned u) { return __uint_as_float(u << 16); }
; DEVI float bf_hi(unsigned u) { return __uint_as_float(u & 0xffff0000u); }
; DEVI float sigmoidf_(float x) { return 1.f / (1.f + __expf(-x)); }
; DEVI u32x4 pack8(f32x4 a, f32x4 b) { u32x4 o; o.x = cvt_pk_bf16(a[0], a[1]); o.y = cvt_pk_bf16(a[2], a[3]); o.z = cvt_pk_bf16(b[0], b[1]); o.w = cvt_pk_bf16(b[2], b[3]); return o; }
; DEVI void gemm_epi(const GJob& jb, int row, int col, f32x4 v0, f32x4 v1) {
;   const int mode = jb.mode;
;   if (mode == 0) { *(u32x4*)((bf16_t*)jb.out + (size_t)row * jb.ldo + col) = pack8(v0, v1); }
;   else if (mode == 1) { float* p = (float*)jb.out + (size_t)row * jb.ldo + col; *(f32x4*)p = v0; *(f32x4*)(p + 4) = v1; }
;   else if (mode == 2) { f32x4 s0, s1; for (int i = 0; i < 4; ++i) { s0[i] = sigmoidf_(v0[i]); s1[i] = sigmoidf_(v1[i]); } *(u32x4*)((bf16_t*)jb.out + (size_t)row * jb.ldo + col) = pack8(s0, s1); }
;   else if (mode == 7) {
;     const u32x4 g = *(const u32x4*)((const bf16_t*)jb.aux + (size_t)row * NGATE + 2 * 2048 + col);
;     const f32x4 g0 = {bf_lo(g.x), bf_hi(g.x), bf_lo(g.y), bf_hi(g.y)}, g1 = {bf_lo(g.z), bf_hi(g.z), bf_lo(g.w), bf_hi(g.w)};
;     *(u32x4*)((bf16_t*)jb.out + (size_t)row * 2048 + col) = pack8(g0 * v0, g1 * v1);
; DEVI void gemm_tile(const GJob& jb, int brow, int bcol, unsigned char* shm_) {
;     ...
;   for (int ai = 0; ai < 2; ++ai)
; #pragma unroll
;     for (int m = 0; m < 4; ++m)
; #pragma unroll
;       for (int bj = 0; bj < 2; ++bj)
;         gemm_epi(jb, brow + ai * HALF + wr * 64 + m * 16 + fr, bcol + bj * HALF + wc * 32 + fq * 8, acc[ai][bj][m][0], acc[ai][bj][m][1]);
.LBB0_424:
	s_setprio 0
	v_or_b32_e32 v0, s43, v159
	v_add_u32_e32 v132, s47, v0
	v_or_b32_e32 v0, s12, v158
	v_ashrrev_i32_e32 v133, 31, v132
	v_or_b32_e32 v130, s68, v0
	s_cmp_eq_u32 s71, 6
	s_cbranch_scc1 .Lepi6
	v_mad_i64_i32 v[136:137], s[0:1], v132, s33, 0
	v_lshlrev_b64 v[134:135], 12, v[132:133]
	s_mov_b64 s[12:13], -1
	s_mov_b64 s[10:11], 0
	s_cmp_lt_i32 s71, 2
	s_mov_b64 s[8:9], 0
	s_cbranch_scc1 .LBB0_433
	s_cmp_gt_i32 s71, 6
	s_cbranch_scc0 .LBB0_429
	s_cmp_eq_u32 s71, 7
	s_mov_b64 s[8:9], -1
	s_cbranch_scc0 .LBB0_428
	v_ashrrev_i32_e32 v131, 31, v130
	v_lshl_add_u64 v[138:139], s[94:95], 0, v[136:137]
	v_lshlrev_b64 v[142:143], 1, v[130:131]
	v_lshl_add_u64 v[138:139], v[138:139], 0, v[142:143]
	v_add_co_u32_e32 v138, vcc, 0x2000, v138
	v_lshl_add_u64 v[144:145], s[90:91], 0, v[134:135]
	s_nop 0
	v_addc_co_u32_e32 v139, vcc, 0, v139, vcc
	global_load_dwordx4 v[138:141], v[138:139], off
	v_lshl_add_u64 v[142:143], v[144:145], 0, v[142:143]
	s_mov_b64 s[8:9], 0
	s_waitcnt vmcnt(0) lgkmcnt(0)
	v_lshlrev_b32_e32 v144, 16, v138
	v_and_b32_e32 v145, 0xffff0000, v138
	v_lshlrev_b32_e32 v138, 16, v139
	v_and_b32_e32 v139, 0xffff0000, v139
	v_lshlrev_b32_e32 v146, 16, v140
	v_and_b32_e32 v147, 0xffff0000, v140
	v_lshlrev_b32_e32 v140, 16, v141
	v_and_b32_e32 v141, 0xffff0000, v141
	v_pk_mul_f32 v[148:149], v[128:129], v[138:139]
	v_pk_mul_f32 v[138:139], v[126:127], v[144:145]
	v_pk_mul_f32 v[144:145], v[124:125], v[140:141]
	v_pk_mul_f32 v[140:141], v[122:123], v[146:147]
	v_cvt_pk_bf16_f32 v138, v138, v139
	v_cvt_pk_bf16_f32 v139, v148, v149
	s_nop 0
	v_cvt_pk_bf16_f32 v140, v140, v141
	v_cvt_pk_bf16_f32 v141, v144, v145
	global_store_dwordx4 v[142:143], v[138:141], off
